# y1 + PEER query GEMM epilogue: the 16 serialized gW/bW flat loads replaced by a 3-deep global_load prefetch ring
# speedup vs baseline: 1.0099x; 1.0099x over previous
.LBB0_725:
	v_lshl_or_b32 v160, s10, 8, v214
	v_ashrrev_i32_e32 v161, 31, v160
	v_lshlrev_b64 v[136:137], 3, v[160:161]
	v_lshl_add_u64 v[130:131], s[46:47], 0, v[136:137]
	v_lshl_add_u64 v[224:225], s[54:55], 0, v[136:137]
	global_load_dwordx4 v[216:219], v[130:131], off
	global_load_dwordx4 v[220:223], v[224:225], off
	global_load_dwordx4 v[242:245], v[130:131], off offset:16
	v_lshl_add_u32 v200, s7, 8, v212
	v_or_b32_e32 v210, 16, v200
	v_ashrrev_i32_e32 v201, 31, v200
	v_ashrrev_i32_e32 v211, 31, v210
	s_mov_b32 s5, 0x3a000000
	s_mov_b32 s4, 0xf800000
	s_mov_b32 s73, 0xc3160ccd
	s_waitcnt vmcnt(2) lgkmcnt(0)
	v_mov_b32_e32 v132, v216
	v_mov_b32_e32 v133, v217
	v_mov_b32_e32 v134, v218
	v_mov_b32_e32 v135, v219
	global_load_dwordx4 v[216:219], v[224:225], off offset:16
	v_cvt_f64_i32_e32 v[148:149], v133
	v_ldexp_f64 v[148:149], v[148:149], 32
	v_cvt_f64_u32_e32 v[132:133], v132
	v_add_f64 v[132:133], v[148:149], v[132:133]
	v_ldexp_f64 v[162:163], v[132:133], s31
	v_lshl_add_u64 v[132:133], s[54:55], 0, v[136:137]
	s_waitcnt vmcnt(2)
	v_mov_b32_e32 v148, v220
	v_mov_b32_e32 v149, v221
	v_mov_b32_e32 v150, v222
	v_mov_b32_e32 v151, v223
	global_load_dwordx4 v[220:223], v[130:131], off offset:32
	v_cvt_f64_i32_e32 v[132:133], v149
	v_ldexp_f64 v[132:133], v[132:133], 32
	v_cvt_f64_u32_e32 v[136:137], v148
	v_add_f64 v[132:133], v[132:133], v[136:137]
	v_ldexp_f64 v[132:133], v[132:133], s31
	v_cvt_f32_f64_e32 v148, v[132:133]
	v_cvt_f64_i32_e32 v[132:133], v135
	v_ldexp_f64 v[132:133], v[132:133], 32
	v_cvt_f64_u32_e32 v[134:135], v134
	v_add_f64 v[132:133], v[132:133], v[134:135]
	v_ldexp_f64 v[164:165], v[132:133], s31
	v_cvt_f64_i32_e32 v[132:133], v151
	v_ldexp_f64 v[132:133], v[132:133], 32
	v_cvt_f64_u32_e32 v[134:135], v150
	v_add_f64 v[132:133], v[132:133], v[134:135]
	v_ldexp_f64 v[132:133], v[132:133], s31
	v_cvt_f32_f64_e32 v149, v[132:133]
	v_or_b32_e32 v136, 2, v160
	v_ashrrev_i32_e32 v137, 31, v136
	s_waitcnt vmcnt(2)
	v_mov_b32_e32 v132, v242
	v_mov_b32_e32 v133, v243
	v_mov_b32_e32 v134, v244
	v_mov_b32_e32 v135, v245
	global_load_dwordx4 v[242:245], v[224:225], off offset:32
	v_cvt_f64_i32_e32 v[150:151], v133
	v_ldexp_f64 v[150:151], v[150:151], 32
	v_cvt_f64_u32_e32 v[132:133], v132
	v_add_f64 v[132:133], v[150:151], v[132:133]
	v_ldexp_f64 v[166:167], v[132:133], s31
	v_lshl_add_u64 v[132:133], v[136:137], 3, s[54:55]
	s_waitcnt vmcnt(2)
	v_mov_b32_e32 v150, v216
	v_mov_b32_e32 v151, v217
	v_mov_b32_e32 v152, v218
	v_mov_b32_e32 v153, v219
	global_load_dwordx4 v[216:219], v[130:131], off offset:48
	v_cvt_f64_i32_e32 v[132:133], v151
	v_ldexp_f64 v[132:133], v[132:133], 32
	v_cvt_f64_u32_e32 v[136:137], v150
	v_add_f64 v[132:133], v[132:133], v[136:137]
	v_ldexp_f64 v[132:133], v[132:133], s31
	v_cvt_f32_f64_e32 v150, v[132:133]
	v_cvt_f64_i32_e32 v[132:133], v135
	v_ldexp_f64 v[132:133], v[132:133], 32
	v_cvt_f64_u32_e32 v[134:135], v134
	v_add_f64 v[132:133], v[132:133], v[134:135]
	v_ldexp_f64 v[168:169], v[132:133], s31
	v_cvt_f64_i32_e32 v[132:133], v153
	v_ldexp_f64 v[132:133], v[132:133], 32
	v_cvt_f64_u32_e32 v[134:135], v152
	v_add_f64 v[132:133], v[132:133], v[134:135]
	v_ldexp_f64 v[132:133], v[132:133], s31
	v_cvt_f32_f64_e32 v151, v[132:133]
	v_or_b32_e32 v136, 4, v160
	v_ashrrev_i32_e32 v137, 31, v136
	s_waitcnt vmcnt(2)
	v_mov_b32_e32 v132, v220
	v_mov_b32_e32 v133, v221
	v_mov_b32_e32 v134, v222
	v_mov_b32_e32 v135, v223
	global_load_dwordx4 v[220:223], v[224:225], off offset:48
	v_cvt_f64_i32_e32 v[152:153], v133
	v_ldexp_f64 v[152:153], v[152:153], 32
	v_cvt_f64_u32_e32 v[132:133], v132
	v_add_f64 v[132:133], v[152:153], v[132:133]
	v_ldexp_f64 v[170:171], v[132:133], s31
	v_lshl_add_u64 v[132:133], v[136:137], 3, s[54:55]
	s_waitcnt vmcnt(2)
	v_mov_b32_e32 v152, v242
	v_mov_b32_e32 v153, v243
	v_mov_b32_e32 v154, v244
	v_mov_b32_e32 v155, v245
	global_load_dwordx4 v[242:245], v[130:131], off offset:1024
	v_cvt_f64_i32_e32 v[132:133], v153
	v_ldexp_f64 v[132:133], v[132:133], 32
	v_cvt_f64_u32_e32 v[136:137], v152
	v_add_f64 v[132:133], v[132:133], v[136:137]
	v_ldexp_f64 v[132:133], v[132:133], s31
	v_cvt_f32_f64_e32 v152, v[132:133]
	v_cvt_f64_i32_e32 v[132:133], v135
	v_ldexp_f64 v[132:133], v[132:133], 32
	v_cvt_f64_u32_e32 v[134:135], v134
	v_add_f64 v[132:133], v[132:133], v[134:135]
	v_ldexp_f64 v[174:175], v[132:133], s31
	v_cvt_f64_i32_e32 v[132:133], v155
	v_ldexp_f64 v[132:133], v[132:133], 32
	v_cvt_f64_u32_e32 v[134:135], v154
	v_add_f64 v[132:133], v[132:133], v[134:135]
	v_ldexp_f64 v[132:133], v[132:133], s31
	v_cvt_f32_f64_e32 v153, v[132:133]
	v_or_b32_e32 v136, 6, v160
	v_ashrrev_i32_e32 v137, 31, v136
	s_waitcnt vmcnt(2)
	v_mov_b32_e32 v132, v216
	v_mov_b32_e32 v133, v217
	v_mov_b32_e32 v134, v218
	v_mov_b32_e32 v135, v219
	global_load_dwordx4 v[216:219], v[224:225], off offset:1024
	v_cvt_f64_i32_e32 v[154:155], v133
	v_ldexp_f64 v[154:155], v[154:155], 32
	v_cvt_f64_u32_e32 v[132:133], v132
	v_add_f64 v[132:133], v[154:155], v[132:133]
	v_ldexp_f64 v[176:177], v[132:133], s31
	v_lshl_add_u64 v[132:133], v[136:137], 3, s[54:55]
	s_waitcnt vmcnt(2)
	v_mov_b32_e32 v154, v220
	v_mov_b32_e32 v155, v221
	v_mov_b32_e32 v156, v222
	v_mov_b32_e32 v157, v223
	global_load_dwordx4 v[220:223], v[130:131], off offset:1040
	v_cvt_f64_i32_e32 v[132:133], v155
	v_ldexp_f64 v[132:133], v[132:133], 32
	v_cvt_f64_u32_e32 v[136:137], v154
	v_add_f64 v[132:133], v[132:133], v[136:137]
	v_ldexp_f64 v[132:133], v[132:133], s31
	v_cvt_f32_f64_e32 v154, v[132:133]
	v_cvt_f64_i32_e32 v[132:133], v135
	v_ldexp_f64 v[132:133], v[132:133], 32
	v_cvt_f64_u32_e32 v[134:135], v134
	v_add_f64 v[132:133], v[132:133], v[134:135]
	v_ldexp_f64 v[178:179], v[132:133], s31
	v_cvt_f64_i32_e32 v[132:133], v157
	v_ldexp_f64 v[132:133], v[132:133], 32
	v_cvt_f64_u32_e32 v[134:135], v156
	v_add_f64 v[132:133], v[132:133], v[134:135]
	v_ldexp_f64 v[132:133], v[132:133], s31
	v_cvt_f32_f64_e32 v155, v[132:133]
	v_or_b32_e32 v136, 0x80, v160
	v_ashrrev_i32_e32 v137, 31, v136
	s_waitcnt vmcnt(2)
	v_mov_b32_e32 v132, v242
	v_mov_b32_e32 v133, v243
	v_mov_b32_e32 v134, v244
	v_mov_b32_e32 v135, v245
	global_load_dwordx4 v[242:245], v[224:225], off offset:1040
	v_cvt_f64_i32_e32 v[156:157], v133
	v_ldexp_f64 v[156:157], v[156:157], 32
	v_cvt_f64_u32_e32 v[132:133], v132
	v_add_f64 v[132:133], v[156:157], v[132:133]
	v_ldexp_f64 v[180:181], v[132:133], s31
	v_lshl_add_u64 v[132:133], v[136:137], 3, s[54:55]
	s_waitcnt vmcnt(2)
	v_mov_b32_e32 v156, v216
	v_mov_b32_e32 v157, v217
	v_mov_b32_e32 v158, v218
	v_mov_b32_e32 v159, v219
	global_load_dwordx4 v[216:219], v[130:131], off offset:1056
	v_cvt_f64_i32_e32 v[132:133], v157
	v_ldexp_f64 v[132:133], v[132:133], 32
	v_cvt_f64_u32_e32 v[136:137], v156
	v_add_f64 v[132:133], v[132:133], v[136:137]
	v_ldexp_f64 v[132:133], v[132:133], s31
	v_cvt_f32_f64_e32 v156, v[132:133]
	v_cvt_f64_i32_e32 v[132:133], v135
	v_ldexp_f64 v[132:133], v[132:133], 32
	v_cvt_f64_u32_e32 v[134:135], v134
	v_add_f64 v[132:133], v[132:133], v[134:135]
	v_ldexp_f64 v[184:185], v[132:133], s31
	v_cvt_f64_i32_e32 v[132:133], v159
	v_ldexp_f64 v[132:133], v[132:133], 32
	v_cvt_f64_u32_e32 v[134:135], v158
	v_add_f64 v[132:133], v[132:133], v[134:135]
	v_ldexp_f64 v[132:133], v[132:133], s31
	v_cvt_f32_f64_e32 v157, v[132:133]
	v_or_b32_e32 v136, 0x82, v160
	v_ashrrev_i32_e32 v137, 31, v136
	s_waitcnt vmcnt(2)
	v_mov_b32_e32 v132, v220
	v_mov_b32_e32 v133, v221
	v_mov_b32_e32 v134, v222
	v_mov_b32_e32 v135, v223
	global_load_dwordx4 v[220:223], v[224:225], off offset:1056
	v_cvt_f64_i32_e32 v[158:159], v133
	v_ldexp_f64 v[158:159], v[158:159], 32
	v_cvt_f64_u32_e32 v[132:133], v132
	v_add_f64 v[132:133], v[158:159], v[132:133]
	v_ldexp_f64 v[196:197], v[132:133], s31
	v_lshl_add_u64 v[132:133], v[136:137], 3, s[54:55]
	s_waitcnt vmcnt(2)
	v_mov_b32_e32 v188, v242
	v_mov_b32_e32 v189, v243
	v_mov_b32_e32 v190, v244
	v_mov_b32_e32 v191, v245
	global_load_dwordx4 v[242:245], v[130:131], off offset:1072
	v_cvt_f64_i32_e32 v[132:133], v189
	v_ldexp_f64 v[132:133], v[132:133], 32
	v_cvt_f64_u32_e32 v[136:137], v188
	v_add_f64 v[132:133], v[132:133], v[136:137]
	v_ldexp_f64 v[132:133], v[132:133], s31
	v_cvt_f32_f64_e32 v158, v[132:133]
	v_cvt_f64_i32_e32 v[132:133], v135
	v_ldexp_f64 v[132:133], v[132:133], 32
	v_cvt_f64_u32_e32 v[134:135], v134
	v_add_f64 v[132:133], v[132:133], v[134:135]
	v_ldexp_f64 v[198:199], v[132:133], s31
	v_cvt_f64_i32_e32 v[132:133], v191
	v_ldexp_f64 v[132:133], v[132:133], 32
	v_cvt_f64_u32_e32 v[134:135], v190
	v_add_f64 v[132:133], v[132:133], v[134:135]
	v_ldexp_f64 v[132:133], v[132:133], s31
	v_cvt_f32_f64_e32 v159, v[132:133]
	v_or_b32_e32 v132, 0x84, v160
	v_ashrrev_i32_e32 v133, 31, v132
	v_lshl_add_u64 v[132:133], v[132:133], 3, s[54:55]
	s_waitcnt vmcnt(2)
	v_mov_b32_e32 v134, v216
	v_mov_b32_e32 v135, v217
	v_mov_b32_e32 v136, v218
	v_mov_b32_e32 v137, v219
	global_load_dwordx4 v[216:219], v[224:225], off offset:1072
	v_cvt_f64_i32_e32 v[172:173], v135
	v_ldexp_f64 v[172:173], v[172:173], 32
	v_cvt_f64_u32_e32 v[134:135], v134
	v_add_f64 v[134:135], v[172:173], v[134:135]
	v_ldexp_f64 v[202:203], v[134:135], s31
	s_waitcnt vmcnt(2)
	v_mov_b32_e32 v132, v220
	v_mov_b32_e32 v133, v221
	v_mov_b32_e32 v134, v222
	v_mov_b32_e32 v135, v223
	v_cvt_f64_i32_e32 v[172:173], v133
	v_ldexp_f64 v[172:173], v[172:173], 32
	v_cvt_f64_u32_e32 v[132:133], v132
	v_add_f64 v[132:133], v[172:173], v[132:133]
	v_ldexp_f64 v[132:133], v[132:133], s31
	v_cvt_f32_f64_e32 v172, v[132:133]
	v_cvt_f64_i32_e32 v[132:133], v137
	v_ldexp_f64 v[132:133], v[132:133], 32
	v_cvt_f64_u32_e32 v[136:137], v136
	v_add_f64 v[132:133], v[132:133], v[136:137]
	v_ldexp_f64 v[204:205], v[132:133], s31
	v_cvt_f64_i32_e32 v[132:133], v135
	v_ldexp_f64 v[132:133], v[132:133], 32
	v_cvt_f64_u32_e32 v[134:135], v134
	v_add_f64 v[132:133], v[132:133], v[134:135]
	v_ldexp_f64 v[132:133], v[132:133], s31
	v_cvt_f32_f64_e32 v173, v[132:133]
	v_or_b32_e32 v134, 0x86, v160
	v_ashrrev_i32_e32 v135, 31, v134
	s_waitcnt vmcnt(1)
	v_mov_b32_e32 v130, v242
	v_mov_b32_e32 v131, v243
	v_mov_b32_e32 v132, v244
	v_mov_b32_e32 v133, v245
	v_cvt_f64_i32_e32 v[136:137], v131
	v_ldexp_f64 v[136:137], v[136:137], 32
	v_cvt_f64_u32_e32 v[130:131], v130
	v_add_f64 v[130:131], v[136:137], v[130:131]
	v_ldexp_f64 v[206:207], v[130:131], s31
	v_lshl_add_u64 v[130:131], v[134:135], 3, s[54:55]
	s_waitcnt vmcnt(0)
	v_mov_b32_e32 v134, v216
	v_mov_b32_e32 v135, v217
	v_mov_b32_e32 v136, v218
	v_mov_b32_e32 v137, v219
	v_cvt_f64_i32_e32 v[130:131], v135
	v_ldexp_f64 v[130:131], v[130:131], 32
	v_cvt_f64_u32_e32 v[134:135], v134
	v_add_f64 v[130:131], v[130:131], v[134:135]
	v_ldexp_f64 v[130:131], v[130:131], s31
	v_cvt_f32_f64_e32 v182, v[130:131]
	v_cvt_f64_i32_e32 v[130:131], v133
	v_ldexp_f64 v[130:131], v[130:131], 32
	v_cvt_f64_u32_e32 v[132:133], v132
	v_add_f64 v[130:131], v[130:131], v[132:133]
	v_ldexp_f64 v[208:209], v[130:131], s31
	v_cvt_f64_i32_e32 v[130:131], v137
	v_ldexp_f64 v[130:131], v[130:131], 32
	v_cvt_f64_u32_e32 v[132:133], v136
	v_add_f64 v[130:131], v[130:131], v[132:133]
	v_ldexp_f64 v[130:131], v[130:131], s31
	v_cvt_f32_f64_e32 v183, v[130:131]
	v_lshl_add_u64 v[130:131], v[210:211], 4, s[44:45]
	v_lshl_add_u64 v[134:135], v[200:201], 4, s[44:45]
	flat_load_dwordx4 v[130:133], v[130:131]
	s_nop 0
	flat_load_dwordx4 v[134:137], v[134:135]
	s_waitcnt vmcnt(0) lgkmcnt(0)
	v_cvt_f64_i32_e32 v[188:189], v135
	v_ldexp_f64 v[188:189], v[188:189], 32
	v_cvt_f64_u32_e32 v[134:135], v134
	v_add_f64 v[134:135], v[188:189], v[134:135]
	v_ldexp_f64 v[134:135], v[134:135], s33
	v_cvt_f32_f64_e32 v1, v[134:135]
	v_cvt_f64_i32_e32 v[134:135], v137
	v_ldexp_f64 v[134:135], v[134:135], 32
	v_cvt_f64_u32_e32 v[136:137], v136
	v_add_f64 v[134:135], v[134:135], v[136:137]
	v_ldexp_f64 v[134:135], v[134:135], s33
	v_mul_f32_e32 v188, 0x3a000000, v1
	v_cvt_f32_f64_e32 v134, v[134:135]
	v_mul_f32_e32 v1, v188, v188
	v_fma_f32 v1, v134, s5, -v1
	v_add_f32_e32 v1, 0x3727c5ac, v1
	v_cmp_gt_f32_e32 vcc, s4, v1
	v_mul_f32_e32 v134, 0x4f800000, v1
	s_nop 0
	v_cndmask_b32_e32 v1, v1, v134, vcc
	v_sqrt_f32_e32 v134, v1
	s_nop 0
	v_add_u32_e32 v135, -1, v134
	v_fma_f32 v136, -v135, v134, v1
	v_cmp_ge_f32_e64 s[38:39], 0, v136
	v_add_u32_e32 v136, 1, v134
	s_nop 0
	v_cndmask_b32_e64 v135, v134, v135, s[38:39]
	v_fma_f32 v134, -v136, v134, v1
	v_cmp_lt_f32_e64 s[38:39], 0, v134
	s_nop 1
	v_cndmask_b32_e64 v134, v135, v136, s[38:39]
	v_mul_f32_e32 v135, 0x37800000, v134
	v_cndmask_b32_e32 v134, v134, v135, vcc
	v_cmp_class_f32_e32 vcc, v1, v229
	s_nop 1
	v_cndmask_b32_e32 v1, v134, v1, vcc
	v_div_scale_f32 v134, s[10:11], v1, v1, 1.0
	v_rcp_f32_e32 v135, v134
	s_nop 0
	v_fma_f32 v136, -v134, v135, 1.0
	v_fmac_f32_e32 v135, v136, v135
	v_div_scale_f32 v136, vcc, 1.0, v1, 1.0
	v_mul_f32_e32 v137, v136, v135
	v_fma_f32 v189, -v134, v137, v136
	v_fmac_f32_e32 v137, v189, v135
	v_fma_f32 v134, -v134, v137, v136
	v_div_fmas_f32 v134, v134, v135, v137
	v_div_fixup_f32 v190, v134, v1, 1.0
	v_lshlrev_b64 v[134:135], 12, v[200:201]
	v_lshl_add_u64 v[136:137], s[42:43], 0, v[134:135]
	v_lshlrev_b64 v[134:135], 1, v[160:161]
	v_lshl_add_u64 v[192:193], v[136:137], 0, v[134:135]
	v_cvt_f32_f64_e64 v137, -v[164:165]
	v_cvt_f32_f64_e64 v136, -v[162:163]
	v_pk_fma_f32 v[160:161], v[136:137], v[188:189], v[126:127] op_sel_hi:[1,0,1]
	v_cvt_f32_f64_e64 v127, -v[168:169]
	v_cvt_f32_f64_e64 v126, -v[166:167]
	v_pk_fma_f32 v[128:129], v[126:127], v[188:189], v[128:129] op_sel_hi:[1,0,1]
	v_pk_fma_f32 v[160:161], v[160:161], v[190:191], v[148:149] op_sel_hi:[1,0,1]
	v_pk_fma_f32 v[162:163], v[128:129], v[190:191], v[150:151] op_sel_hi:[1,0,1]
	v_cvt_f32_f64_e64 v129, -v[174:175]
	v_cvt_f32_f64_e64 v128, -v[170:171]
	v_pk_fma_f32 v[164:165], v[128:129], v[188:189], v[122:123] op_sel_hi:[1,0,1]
	v_cvt_f32_f64_e64 v123, -v[178:179]
	v_cvt_f32_f64_e64 v122, -v[176:177]
	v_pk_fma_f32 v[124:125], v[122:123], v[188:189], v[124:125] op_sel_hi:[1,0,1]
	v_pk_fma_f32 v[164:165], v[164:165], v[190:191], v[152:153] op_sel_hi:[1,0,1]
	v_pk_fma_f32 v[124:125], v[124:125], v[190:191], v[154:155] op_sel_hi:[1,0,1]
	v_cvt_pk_bf16_f32 v160, v160, v161
	v_cvt_pk_bf16_f32 v161, v162, v163
	v_cvt_pk_bf16_f32 v162, v164, v165
	v_cvt_pk_bf16_f32 v163, v124, v125
	v_cvt_f32_f64_e64 v125, -v[184:185]
	v_cvt_f32_f64_e64 v124, -v[180:181]
	flat_store_dwordx4 v[192:193], v[160:163]
	s_nop 1
	v_pk_fma_f32 v[160:161], v[124:125], v[188:189], v[118:119] op_sel_hi:[1,0,1]
	v_cvt_f32_f64_e64 v119, -v[198:199]
	v_cvt_f32_f64_e64 v118, -v[196:197]
	v_pk_fma_f32 v[120:121], v[118:119], v[188:189], v[120:121] op_sel_hi:[1,0,1]
	v_pk_fma_f32 v[160:161], v[160:161], v[190:191], v[156:157] op_sel_hi:[1,0,1]
	v_pk_fma_f32 v[162:163], v[120:121], v[190:191], v[158:159] op_sel_hi:[1,0,1]
	v_cvt_f32_f64_e64 v121, -v[204:205]
	v_cvt_f32_f64_e64 v120, -v[202:203]
	v_pk_fma_f32 v[164:165], v[120:121], v[188:189], v[114:115] op_sel_hi:[1,0,1]
	v_cvt_f32_f64_e64 v115, -v[208:209]
	v_cvt_f32_f64_e64 v114, -v[206:207]
	v_pk_fma_f32 v[116:117], v[114:115], v[188:189], v[116:117] op_sel_hi:[1,0,1]
	v_pk_fma_f32 v[164:165], v[164:165], v[190:191], v[172:173] op_sel_hi:[1,0,1]
	v_pk_fma_f32 v[116:117], v[116:117], v[190:191], v[182:183] op_sel_hi:[1,0,1]
	v_cvt_pk_bf16_f32 v160, v160, v161
	v_cvt_pk_bf16_f32 v161, v162, v163
	v_cvt_pk_bf16_f32 v163, v116, v117
	v_or_b32_e32 v116, 32, v200
	v_cvt_pk_bf16_f32 v162, v164, v165
	v_ashrrev_i32_e32 v117, 31, v116
	flat_store_dwordx4 v[192:193], v[160:163] offset:256
	v_cvt_f64_i32_e32 v[164:165], v131
	v_ldexp_f64 v[164:165], v[164:165], 32
	v_lshl_add_u64 v[160:161], v[116:117], 4, s[44:45]
	flat_load_dwordx4 v[160:163], v[160:161]
	v_cvt_f64_u32_e32 v[130:131], v130
	v_add_f64 v[130:131], v[164:165], v[130:131]
	v_ldexp_f64 v[130:131], v[130:131], s33
	v_cvt_f32_f64_e32 v1, v[130:131]
	v_cvt_f64_i32_e32 v[130:131], v133
	v_ldexp_f64 v[130:131], v[130:131], 32
	v_cvt_f64_u32_e32 v[132:133], v132
	v_add_f64 v[130:131], v[130:131], v[132:133]
	v_ldexp_f64 v[130:131], v[130:131], s33
	v_cvt_f32_f64_e32 v131, v[130:131]
	v_mul_f32_e32 v130, 0x3a000000, v1
	v_mul_f32_e32 v1, v130, v130
	v_fma_f32 v1, v131, s5, -v1
	v_add_f32_e32 v1, 0x3727c5ac, v1
	v_cmp_gt_f32_e32 vcc, s4, v1
	v_mul_f32_e32 v131, 0x4f800000, v1
	s_nop 0
	v_cndmask_b32_e32 v1, v1, v131, vcc
	v_sqrt_f32_e32 v131, v1
	s_nop 0
	v_add_u32_e32 v132, -1, v131
	v_fma_f32 v133, -v132, v131, v1
	v_cmp_ge_f32_e64 s[38:39], 0, v133
	v_add_u32_e32 v133, 1, v131
	s_nop 0
	v_cndmask_b32_e64 v132, v131, v132, s[38:39]
	v_fma_f32 v131, -v133, v131, v1
	v_cmp_lt_f32_e64 s[38:39], 0, v131
	s_nop 1
	v_cndmask_b32_e64 v131, v132, v133, s[38:39]
	v_mul_f32_e32 v132, 0x37800000, v131
	v_cndmask_b32_e32 v131, v131, v132, vcc
	v_cmp_class_f32_e32 vcc, v1, v229
	s_nop 1
	v_cndmask_b32_e32 v1, v131, v1, vcc
	v_div_scale_f32 v131, s[10:11], v1, v1, 1.0
	v_rcp_f32_e32 v132, v131
	s_nop 0
	v_fma_f32 v133, -v131, v132, 1.0
	v_fmac_f32_e32 v132, v133, v132
	v_div_scale_f32 v133, vcc, 1.0, v1, 1.0
	v_mul_f32_e32 v164, v133, v132
	v_fma_f32 v165, -v131, v164, v133
	v_fmac_f32_e32 v164, v165, v132
	v_fma_f32 v131, -v131, v164, v133
	v_div_fmas_f32 v131, v131, v132, v164
	v_div_fixup_f32 v132, v131, v1, 1.0
	v_lshlrev_b64 v[164:165], 12, v[210:211]
	v_pk_fma_f32 v[110:111], v[136:137], v[130:131], v[110:111] op_sel_hi:[1,0,1]
	v_pk_fma_f32 v[112:113], v[126:127], v[130:131], v[112:113] op_sel_hi:[1,0,1]
	v_pk_fma_f32 v[106:107], v[128:129], v[130:131], v[106:107] op_sel_hi:[1,0,1]
	v_pk_fma_f32 v[108:109], v[122:123], v[130:131], v[108:109] op_sel_hi:[1,0,1]
	v_lshl_add_u64 v[164:165], s[42:43], 0, v[164:165]
	v_pk_fma_f32 v[112:113], v[112:113], v[132:133], v[150:151] op_sel_hi:[1,0,1]
	v_pk_fma_f32 v[110:111], v[110:111], v[132:133], v[148:149] op_sel_hi:[1,0,1]
	v_pk_fma_f32 v[166:167], v[108:109], v[132:133], v[154:155] op_sel_hi:[1,0,1]
	v_pk_fma_f32 v[108:109], v[106:107], v[132:133], v[152:153] op_sel_hi:[1,0,1]
	v_pk_fma_f32 v[102:103], v[124:125], v[130:131], v[102:103] op_sel_hi:[1,0,1]
	v_lshl_add_u64 v[164:165], v[164:165], 0, v[134:135]
	v_cvt_pk_bf16_f32 v106, v110, v111
	v_cvt_pk_bf16_f32 v107, v112, v113
	v_cvt_pk_bf16_f32 v108, v108, v109
	v_cvt_pk_bf16_f32 v109, v166, v167
	v_pk_fma_f32 v[104:105], v[118:119], v[130:131], v[104:105] op_sel_hi:[1,0,1]
	v_pk_fma_f32 v[102:103], v[102:103], v[132:133], v[156:157] op_sel_hi:[1,0,1]
	v_pk_fma_f32 v[98:99], v[120:121], v[130:131], v[98:99] op_sel_hi:[1,0,1]
	v_pk_fma_f32 v[100:101], v[114:115], v[130:131], v[100:101] op_sel_hi:[1,0,1]
	flat_store_dwordx4 v[164:165], v[106:109]
	v_pk_fma_f32 v[104:105], v[104:105], v[132:133], v[158:159] op_sel_hi:[1,0,1]
	s_nop 0
	v_pk_fma_f32 v[106:107], v[100:101], v[132:133], v[182:183] op_sel_hi:[1,0,1]
	v_pk_fma_f32 v[100:101], v[98:99], v[132:133], v[172:173] op_sel_hi:[1,0,1]
	v_cvt_pk_bf16_f32 v98, v102, v103
	v_or_b32_e32 v102, 48, v200
	v_cvt_pk_bf16_f32 v99, v104, v105
	v_cvt_pk_bf16_f32 v100, v100, v101
	v_cvt_pk_bf16_f32 v101, v106, v107
	v_ashrrev_i32_e32 v103, 31, v102
	flat_store_dwordx4 v[164:165], v[98:101] offset:256
	s_waitcnt vmcnt(0) lgkmcnt(0)
	v_cvt_f64_i32_e32 v[104:105], v161
	v_ldexp_f64 v[104:105], v[104:105], 32
	v_lshl_add_u64 v[98:99], v[102:103], 4, s[44:45]
	flat_load_dwordx4 v[98:101], v[98:99]
	v_cvt_f64_u32_e32 v[106:107], v160
	v_add_f64 v[104:105], v[104:105], v[106:107]
	v_ldexp_f64 v[104:105], v[104:105], s33
	v_cvt_f32_f64_e32 v1, v[104:105]
	v_cvt_f64_i32_e32 v[104:105], v163
	v_ldexp_f64 v[104:105], v[104:105], 32
	v_cvt_f64_u32_e32 v[106:107], v162
	v_add_f64 v[104:105], v[104:105], v[106:107]
	v_ldexp_f64 v[104:105], v[104:105], s33
	v_cvt_f32_f64_e32 v105, v[104:105]
	v_mul_f32_e32 v104, 0x3a000000, v1
	v_mul_f32_e32 v1, v104, v104
	v_fma_f32 v1, v105, s5, -v1
	v_add_f32_e32 v1, 0x3727c5ac, v1
	v_cmp_gt_f32_e32 vcc, s4, v1
	v_mul_f32_e32 v105, 0x4f800000, v1
	s_nop 0
	v_cndmask_b32_e32 v1, v1, v105, vcc
	v_sqrt_f32_e32 v105, v1
	s_nop 0
	v_add_u32_e32 v106, -1, v105
	v_fma_f32 v107, -v106, v105, v1
	v_cmp_ge_f32_e64 s[38:39], 0, v107
	v_add_u32_e32 v107, 1, v105
	s_nop 0
	v_cndmask_b32_e64 v106, v105, v106, s[38:39]
	v_fma_f32 v105, -v107, v105, v1
	v_cmp_lt_f32_e64 s[38:39], 0, v105
	s_nop 1
	v_cndmask_b32_e64 v105, v106, v107, s[38:39]
	v_mul_f32_e32 v106, 0x37800000, v105
	v_cndmask_b32_e32 v105, v105, v106, vcc
	v_cmp_class_f32_e32 vcc, v1, v229
	s_nop 1
	v_cndmask_b32_e32 v1, v105, v1, vcc
	v_div_scale_f32 v105, s[10:11], v1, v1, 1.0
	v_rcp_f32_e32 v106, v105
	s_nop 0
	v_fma_f32 v107, -v105, v106, 1.0
	v_fmac_f32_e32 v106, v107, v106
	v_div_scale_f32 v107, vcc, 1.0, v1, 1.0
	v_mul_f32_e32 v108, v107, v106
	v_fma_f32 v109, -v105, v108, v107
	v_fmac_f32_e32 v108, v109, v106
	v_fma_f32 v105, -v105, v108, v107
	v_div_fmas_f32 v105, v105, v106, v108
	v_div_fixup_f32 v106, v105, v1, 1.0
	v_lshlrev_b64 v[108:109], 12, v[116:117]
	v_pk_fma_f32 v[94:95], v[136:137], v[104:105], v[94:95] op_sel_hi:[1,0,1]
	v_pk_fma_f32 v[96:97], v[126:127], v[104:105], v[96:97] op_sel_hi:[1,0,1]
	v_pk_fma_f32 v[90:91], v[128:129], v[104:105], v[90:91] op_sel_hi:[1,0,1]
	v_pk_fma_f32 v[92:93], v[122:123], v[104:105], v[92:93] op_sel_hi:[1,0,1]
	v_lshl_add_u64 v[108:109], s[42:43], 0, v[108:109]
	v_pk_fma_f32 v[96:97], v[96:97], v[106:107], v[150:151] op_sel_hi:[1,0,1]
	v_pk_fma_f32 v[94:95], v[94:95], v[106:107], v[148:149] op_sel_hi:[1,0,1]
	v_pk_fma_f32 v[110:111], v[92:93], v[106:107], v[154:155] op_sel_hi:[1,0,1]
	v_pk_fma_f32 v[92:93], v[90:91], v[106:107], v[152:153] op_sel_hi:[1,0,1]
	v_pk_fma_f32 v[86:87], v[124:125], v[104:105], v[86:87] op_sel_hi:[1,0,1]
	v_lshl_add_u64 v[108:109], v[108:109], 0, v[134:135]
	v_cvt_pk_bf16_f32 v90, v94, v95
	v_cvt_pk_bf16_f32 v91, v96, v97
	v_cvt_pk_bf16_f32 v92, v92, v93
	v_cvt_pk_bf16_f32 v93, v110, v111
	v_pk_fma_f32 v[88:89], v[118:119], v[104:105], v[88:89] op_sel_hi:[1,0,1]
	v_pk_fma_f32 v[86:87], v[86:87], v[106:107], v[156:157] op_sel_hi:[1,0,1]
	v_pk_fma_f32 v[82:83], v[120:121], v[104:105], v[82:83] op_sel_hi:[1,0,1]
	v_pk_fma_f32 v[84:85], v[114:115], v[104:105], v[84:85] op_sel_hi:[1,0,1]
	flat_store_dwordx4 v[108:109], v[90:93]
	v_pk_fma_f32 v[88:89], v[88:89], v[106:107], v[158:159] op_sel_hi:[1,0,1]
	s_nop 0
	v_pk_fma_f32 v[90:91], v[84:85], v[106:107], v[182:183] op_sel_hi:[1,0,1]
	v_pk_fma_f32 v[84:85], v[82:83], v[106:107], v[172:173] op_sel_hi:[1,0,1]
	v_cvt_pk_bf16_f32 v82, v86, v87
	v_add_u32_e32 v86, 0x80, v200
	v_cvt_pk_bf16_f32 v83, v88, v89
	v_cvt_pk_bf16_f32 v84, v84, v85
	v_cvt_pk_bf16_f32 v85, v90, v91
	v_ashrrev_i32_e32 v87, 31, v86
	flat_store_dwordx4 v[108:109], v[82:85] offset:256
	s_waitcnt vmcnt(0) lgkmcnt(0)
	v_cvt_f64_i32_e32 v[88:89], v99
	v_ldexp_f64 v[88:89], v[88:89], 32
	v_lshl_add_u64 v[82:83], v[86:87], 4, s[44:45]
	flat_load_dwordx4 v[82:85], v[82:83]
	v_cvt_f64_u32_e32 v[90:91], v98
	v_add_f64 v[88:89], v[88:89], v[90:91]
	v_ldexp_f64 v[88:89], v[88:89], s33
	v_cvt_f32_f64_e32 v1, v[88:89]
	v_cvt_f64_i32_e32 v[88:89], v101
	v_ldexp_f64 v[88:89], v[88:89], 32
	v_cvt_f64_u32_e32 v[90:91], v100
	v_add_f64 v[88:89], v[88:89], v[90:91]
	v_ldexp_f64 v[88:89], v[88:89], s33
	v_cvt_f32_f64_e32 v89, v[88:89]
	v_mul_f32_e32 v88, 0x3a000000, v1
	v_mul_f32_e32 v1, v88, v88
	v_fma_f32 v1, v89, s5, -v1
	v_add_f32_e32 v1, 0x3727c5ac, v1
	v_cmp_gt_f32_e32 vcc, s4, v1
	v_mul_f32_e32 v89, 0x4f800000, v1
	s_nop 0
	v_cndmask_b32_e32 v1, v1, v89, vcc
	v_sqrt_f32_e32 v89, v1
	s_nop 0
	v_add_u32_e32 v90, -1, v89
	v_fma_f32 v91, -v90, v89, v1
	v_cmp_ge_f32_e64 s[38:39], 0, v91
	v_add_u32_e32 v91, 1, v89
	s_nop 0
	v_cndmask_b32_e64 v90, v89, v90, s[38:39]
	v_fma_f32 v89, -v91, v89, v1
	v_cmp_lt_f32_e64 s[38:39], 0, v89
	s_nop 1
	v_cndmask_b32_e64 v89, v90, v91, s[38:39]
	v_mul_f32_e32 v90, 0x37800000, v89
	v_cndmask_b32_e32 v89, v89, v90, vcc
	v_cmp_class_f32_e32 vcc, v1, v229
	s_nop 1
	v_cndmask_b32_e32 v1, v89, v1, vcc
	v_div_scale_f32 v89, s[10:11], v1, v1, 1.0
	v_rcp_f32_e32 v90, v89
	s_nop 0
	v_fma_f32 v91, -v89, v90, 1.0
	v_fmac_f32_e32 v90, v91, v90
	v_div_scale_f32 v91, vcc, 1.0, v1, 1.0
	v_mul_f32_e32 v92, v91, v90
	v_fma_f32 v93, -v89, v92, v91
	v_fmac_f32_e32 v92, v93, v90
	v_fma_f32 v89, -v89, v92, v91
	v_div_fmas_f32 v89, v89, v90, v92
	v_div_fixup_f32 v90, v89, v1, 1.0
	v_lshlrev_b64 v[92:93], 12, v[102:103]
	v_pk_fma_f32 v[78:79], v[136:137], v[88:89], v[78:79] op_sel_hi:[1,0,1]
	v_pk_fma_f32 v[80:81], v[126:127], v[88:89], v[80:81] op_sel_hi:[1,0,1]
	v_pk_fma_f32 v[74:75], v[128:129], v[88:89], v[74:75] op_sel_hi:[1,0,1]
	v_pk_fma_f32 v[76:77], v[122:123], v[88:89], v[76:77] op_sel_hi:[1,0,1]
	v_lshl_add_u64 v[92:93], s[42:43], 0, v[92:93]
	v_pk_fma_f32 v[80:81], v[80:81], v[90:91], v[150:151] op_sel_hi:[1,0,1]
	v_pk_fma_f32 v[78:79], v[78:79], v[90:91], v[148:149] op_sel_hi:[1,0,1]
	v_pk_fma_f32 v[94:95], v[76:77], v[90:91], v[154:155] op_sel_hi:[1,0,1]
	v_pk_fma_f32 v[76:77], v[74:75], v[90:91], v[152:153] op_sel_hi:[1,0,1]
	v_pk_fma_f32 v[70:71], v[124:125], v[88:89], v[70:71] op_sel_hi:[1,0,1]
	v_lshl_add_u64 v[92:93], v[92:93], 0, v[134:135]
	v_cvt_pk_bf16_f32 v74, v78, v79
	v_cvt_pk_bf16_f32 v75, v80, v81
	v_cvt_pk_bf16_f32 v76, v76, v77
	v_cvt_pk_bf16_f32 v77, v94, v95
	v_pk_fma_f32 v[72:73], v[118:119], v[88:89], v[72:73] op_sel_hi:[1,0,1]
	v_pk_fma_f32 v[70:71], v[70:71], v[90:91], v[156:157] op_sel_hi:[1,0,1]
	v_pk_fma_f32 v[66:67], v[120:121], v[88:89], v[66:67] op_sel_hi:[1,0,1]
	v_pk_fma_f32 v[68:69], v[114:115], v[88:89], v[68:69] op_sel_hi:[1,0,1]
	flat_store_dwordx4 v[92:93], v[74:77]
	v_pk_fma_f32 v[72:73], v[72:73], v[90:91], v[158:159] op_sel_hi:[1,0,1]
	s_nop 0
	v_pk_fma_f32 v[74:75], v[68:69], v[90:91], v[182:183] op_sel_hi:[1,0,1]
	v_pk_fma_f32 v[68:69], v[66:67], v[90:91], v[172:173] op_sel_hi:[1,0,1]
	v_cvt_pk_bf16_f32 v66, v70, v71
	v_add_u32_e32 v70, 0x90, v200
	v_cvt_pk_bf16_f32 v67, v72, v73
	v_cvt_pk_bf16_f32 v68, v68, v69
	v_cvt_pk_bf16_f32 v69, v74, v75
	v_ashrrev_i32_e32 v71, 31, v70
	flat_store_dwordx4 v[92:93], v[66:69] offset:256
	s_waitcnt vmcnt(0) lgkmcnt(0)
	v_cvt_f64_i32_e32 v[72:73], v83
	v_ldexp_f64 v[72:73], v[72:73], 32
	v_lshl_add_u64 v[66:67], v[70:71], 4, s[44:45]
	flat_load_dwordx4 v[66:69], v[66:67]
	v_cvt_f64_u32_e32 v[74:75], v82
	v_add_f64 v[72:73], v[72:73], v[74:75]
	v_ldexp_f64 v[72:73], v[72:73], s33
	v_cvt_f32_f64_e32 v1, v[72:73]
	v_cvt_f64_i32_e32 v[72:73], v85
	v_ldexp_f64 v[72:73], v[72:73], 32
	v_cvt_f64_u32_e32 v[74:75], v84
	v_add_f64 v[72:73], v[72:73], v[74:75]
	v_ldexp_f64 v[72:73], v[72:73], s33
	v_cvt_f32_f64_e32 v73, v[72:73]
	v_mul_f32_e32 v72, 0x3a000000, v1
	v_mul_f32_e32 v1, v72, v72
	v_fma_f32 v1, v73, s5, -v1
	v_add_f32_e32 v1, 0x3727c5ac, v1
	v_cmp_gt_f32_e32 vcc, s4, v1
	v_mul_f32_e32 v73, 0x4f800000, v1
	s_nop 0
	v_cndmask_b32_e32 v1, v1, v73, vcc
	v_sqrt_f32_e32 v73, v1
	s_nop 0
	v_add_u32_e32 v74, -1, v73
	v_fma_f32 v75, -v74, v73, v1
	v_cmp_ge_f32_e64 s[38:39], 0, v75
	v_add_u32_e32 v75, 1, v73
	s_nop 0
	v_cndmask_b32_e64 v74, v73, v74, s[38:39]
	v_fma_f32 v73, -v75, v73, v1
	v_cmp_lt_f32_e64 s[38:39], 0, v73
	s_nop 1
	v_cndmask_b32_e64 v73, v74, v75, s[38:39]
	v_mul_f32_e32 v74, 0x37800000, v73
	v_cndmask_b32_e32 v73, v73, v74, vcc
	v_cmp_class_f32_e32 vcc, v1, v229
	s_nop 1
	v_cndmask_b32_e32 v1, v73, v1, vcc
	v_div_scale_f32 v73, s[10:11], v1, v1, 1.0
	v_rcp_f32_e32 v74, v73
	s_nop 0
	v_fma_f32 v75, -v73, v74, 1.0
	v_fmac_f32_e32 v74, v75, v74
	v_div_scale_f32 v75, vcc, 1.0, v1, 1.0
	v_mul_f32_e32 v76, v75, v74
	v_fma_f32 v77, -v73, v76, v75
	v_fmac_f32_e32 v76, v77, v74
	v_fma_f32 v73, -v73, v76, v75
	v_div_fmas_f32 v73, v73, v74, v76
	v_div_fixup_f32 v74, v73, v1, 1.0
	v_lshlrev_b64 v[76:77], 12, v[86:87]
	v_pk_fma_f32 v[62:63], v[136:137], v[72:73], v[62:63] op_sel_hi:[1,0,1]
	v_pk_fma_f32 v[64:65], v[126:127], v[72:73], v[64:65] op_sel_hi:[1,0,1]
	v_pk_fma_f32 v[58:59], v[128:129], v[72:73], v[58:59] op_sel_hi:[1,0,1]
	v_pk_fma_f32 v[60:61], v[122:123], v[72:73], v[60:61] op_sel_hi:[1,0,1]
	v_lshl_add_u64 v[76:77], s[42:43], 0, v[76:77]
	v_pk_fma_f32 v[64:65], v[64:65], v[74:75], v[150:151] op_sel_hi:[1,0,1]
	v_pk_fma_f32 v[62:63], v[62:63], v[74:75], v[148:149] op_sel_hi:[1,0,1]
	v_pk_fma_f32 v[78:79], v[60:61], v[74:75], v[154:155] op_sel_hi:[1,0,1]
	v_pk_fma_f32 v[60:61], v[58:59], v[74:75], v[152:153] op_sel_hi:[1,0,1]
	v_pk_fma_f32 v[54:55], v[124:125], v[72:73], v[54:55] op_sel_hi:[1,0,1]
	v_lshl_add_u64 v[76:77], v[76:77], 0, v[134:135]
	v_cvt_pk_bf16_f32 v58, v62, v63
	v_cvt_pk_bf16_f32 v59, v64, v65
	v_cvt_pk_bf16_f32 v60, v60, v61
	v_cvt_pk_bf16_f32 v61, v78, v79
	v_pk_fma_f32 v[56:57], v[118:119], v[72:73], v[56:57] op_sel_hi:[1,0,1]
	v_pk_fma_f32 v[54:55], v[54:55], v[74:75], v[156:157] op_sel_hi:[1,0,1]
	v_pk_fma_f32 v[50:51], v[120:121], v[72:73], v[50:51] op_sel_hi:[1,0,1]
	v_pk_fma_f32 v[52:53], v[114:115], v[72:73], v[52:53] op_sel_hi:[1,0,1]
	flat_store_dwordx4 v[76:77], v[58:61]
	v_pk_fma_f32 v[56:57], v[56:57], v[74:75], v[158:159] op_sel_hi:[1,0,1]
	s_nop 0
	v_pk_fma_f32 v[58:59], v[52:53], v[74:75], v[182:183] op_sel_hi:[1,0,1]
	v_pk_fma_f32 v[52:53], v[50:51], v[74:75], v[172:173] op_sel_hi:[1,0,1]
	v_cvt_pk_bf16_f32 v50, v54, v55
	v_add_u32_e32 v54, 0xa0, v200
	v_cvt_pk_bf16_f32 v51, v56, v57
	v_cvt_pk_bf16_f32 v52, v52, v53
	v_cvt_pk_bf16_f32 v53, v58, v59
	v_ashrrev_i32_e32 v55, 31, v54
	flat_store_dwordx4 v[76:77], v[50:53] offset:256
	s_waitcnt vmcnt(0) lgkmcnt(0)
	v_cvt_f64_i32_e32 v[56:57], v67
	v_ldexp_f64 v[56:57], v[56:57], 32
	v_lshl_add_u64 v[50:51], v[54:55], 4, s[44:45]
	flat_load_dwordx4 v[50:53], v[50:51]
	v_cvt_f64_u32_e32 v[58:59], v66
	v_add_f64 v[56:57], v[56:57], v[58:59]
	v_ldexp_f64 v[56:57], v[56:57], s33
	v_cvt_f32_f64_e32 v1, v[56:57]
	v_cvt_f64_i32_e32 v[56:57], v69
	v_ldexp_f64 v[56:57], v[56:57], 32
	v_cvt_f64_u32_e32 v[58:59], v68
	v_add_f64 v[56:57], v[56:57], v[58:59]
	v_ldexp_f64 v[56:57], v[56:57], s33
	v_cvt_f32_f64_e32 v57, v[56:57]
	v_mul_f32_e32 v56, 0x3a000000, v1
	v_mul_f32_e32 v1, v56, v56
	v_fma_f32 v1, v57, s5, -v1
	v_add_f32_e32 v1, 0x3727c5ac, v1
	v_cmp_gt_f32_e32 vcc, s4, v1
	v_mul_f32_e32 v57, 0x4f800000, v1
	s_nop 0
	v_cndmask_b32_e32 v1, v1, v57, vcc
	v_sqrt_f32_e32 v57, v1
	s_nop 0
	v_add_u32_e32 v58, -1, v57
	v_fma_f32 v59, -v58, v57, v1
	v_cmp_ge_f32_e64 s[38:39], 0, v59
	v_add_u32_e32 v59, 1, v57
	s_nop 0
	v_cndmask_b32_e64 v58, v57, v58, s[38:39]
	v_fma_f32 v57, -v59, v57, v1
	v_cmp_lt_f32_e64 s[38:39], 0, v57
	s_nop 1
	v_cndmask_b32_e64 v57, v58, v59, s[38:39]
	v_mul_f32_e32 v58, 0x37800000, v57
	v_cndmask_b32_e32 v57, v57, v58, vcc
	v_cmp_class_f32_e32 vcc, v1, v229
	s_nop 1
	v_cndmask_b32_e32 v1, v57, v1, vcc
	v_div_scale_f32 v57, s[10:11], v1, v1, 1.0
	v_rcp_f32_e32 v58, v57
	s_nop 0
	v_fma_f32 v59, -v57, v58, 1.0
	v_fmac_f32_e32 v58, v59, v58
	v_div_scale_f32 v59, vcc, 1.0, v1, 1.0
	v_mul_f32_e32 v60, v59, v58
	v_fma_f32 v61, -v57, v60, v59
	v_fmac_f32_e32 v60, v61, v58
	v_fma_f32 v57, -v57, v60, v59
	v_div_fmas_f32 v57, v57, v58, v60
	v_div_fixup_f32 v58, v57, v1, 1.0
	v_lshlrev_b64 v[60:61], 12, v[70:71]
	v_pk_fma_f32 v[46:47], v[136:137], v[56:57], v[46:47] op_sel_hi:[1,0,1]
	v_pk_fma_f32 v[48:49], v[126:127], v[56:57], v[48:49] op_sel_hi:[1,0,1]
	v_pk_fma_f32 v[42:43], v[128:129], v[56:57], v[42:43] op_sel_hi:[1,0,1]
	v_pk_fma_f32 v[44:45], v[122:123], v[56:57], v[44:45] op_sel_hi:[1,0,1]
	v_lshl_add_u64 v[60:61], s[42:43], 0, v[60:61]
	v_pk_fma_f32 v[48:49], v[48:49], v[58:59], v[150:151] op_sel_hi:[1,0,1]
	v_pk_fma_f32 v[46:47], v[46:47], v[58:59], v[148:149] op_sel_hi:[1,0,1]
	v_pk_fma_f32 v[62:63], v[44:45], v[58:59], v[154:155] op_sel_hi:[1,0,1]
	v_pk_fma_f32 v[44:45], v[42:43], v[58:59], v[152:153] op_sel_hi:[1,0,1]
	v_pk_fma_f32 v[38:39], v[124:125], v[56:57], v[38:39] op_sel_hi:[1,0,1]
	v_lshl_add_u64 v[60:61], v[60:61], 0, v[134:135]
	v_cvt_pk_bf16_f32 v42, v46, v47
	v_cvt_pk_bf16_f32 v43, v48, v49
	v_cvt_pk_bf16_f32 v44, v44, v45
	v_cvt_pk_bf16_f32 v45, v62, v63
	v_pk_fma_f32 v[40:41], v[118:119], v[56:57], v[40:41] op_sel_hi:[1,0,1]
	v_pk_fma_f32 v[38:39], v[38:39], v[58:59], v[156:157] op_sel_hi:[1,0,1]
	v_pk_fma_f32 v[34:35], v[120:121], v[56:57], v[34:35] op_sel_hi:[1,0,1]
	v_pk_fma_f32 v[36:37], v[114:115], v[56:57], v[36:37] op_sel_hi:[1,0,1]
	flat_store_dwordx4 v[60:61], v[42:45]
	v_pk_fma_f32 v[40:41], v[40:41], v[58:59], v[158:159] op_sel_hi:[1,0,1]
	s_nop 0
	v_pk_fma_f32 v[42:43], v[36:37], v[58:59], v[182:183] op_sel_hi:[1,0,1]
	v_pk_fma_f32 v[36:37], v[34:35], v[58:59], v[172:173] op_sel_hi:[1,0,1]
	v_cvt_pk_bf16_f32 v34, v38, v39
	v_add_u32_e32 v38, 0xb0, v200
	v_cvt_pk_bf16_f32 v35, v40, v41
	v_cvt_pk_bf16_f32 v36, v36, v37
	v_cvt_pk_bf16_f32 v37, v42, v43
	v_ashrrev_i32_e32 v39, 31, v38
	flat_store_dwordx4 v[60:61], v[34:37] offset:256
	s_waitcnt vmcnt(0) lgkmcnt(0)
	v_cvt_f64_i32_e32 v[40:41], v51
	v_ldexp_f64 v[40:41], v[40:41], 32
	v_lshl_add_u64 v[34:35], v[38:39], 4, s[44:45]
	flat_load_dwordx4 v[34:37], v[34:35]
	v_cvt_f64_u32_e32 v[42:43], v50
	v_add_f64 v[40:41], v[40:41], v[42:43]
	v_ldexp_f64 v[40:41], v[40:41], s33
	v_cvt_f32_f64_e32 v1, v[40:41]
	v_cvt_f64_i32_e32 v[40:41], v53
	v_ldexp_f64 v[40:41], v[40:41], 32
	v_cvt_f64_u32_e32 v[42:43], v52
	v_add_f64 v[40:41], v[40:41], v[42:43]
	v_ldexp_f64 v[40:41], v[40:41], s33
	v_cvt_f32_f64_e32 v41, v[40:41]
	v_mul_f32_e32 v40, 0x3a000000, v1
	v_mul_f32_e32 v1, v40, v40
	v_fma_f32 v1, v41, s5, -v1
	v_add_f32_e32 v1, 0x3727c5ac, v1
	v_cmp_gt_f32_e32 vcc, s4, v1
	v_mul_f32_e32 v41, 0x4f800000, v1
	s_nop 0
	v_cndmask_b32_e32 v1, v1, v41, vcc
	v_sqrt_f32_e32 v41, v1
	s_nop 0
	v_add_u32_e32 v42, -1, v41
	v_fma_f32 v43, -v42, v41, v1
	v_cmp_ge_f32_e64 s[38:39], 0, v43
	v_add_u32_e32 v43, 1, v41
	s_nop 0
	v_cndmask_b32_e64 v42, v41, v42, s[38:39]
	v_fma_f32 v41, -v43, v41, v1
	v_cmp_lt_f32_e64 s[38:39], 0, v41
	s_nop 1
	v_cndmask_b32_e64 v41, v42, v43, s[38:39]
	v_mul_f32_e32 v42, 0x37800000, v41
	v_cndmask_b32_e32 v41, v41, v42, vcc
	v_cmp_class_f32_e32 vcc, v1, v229
	s_nop 1
	v_cndmask_b32_e32 v1, v41, v1, vcc
	v_div_scale_f32 v41, s[10:11], v1, v1, 1.0
	v_rcp_f32_e32 v42, v41
	s_nop 0
	v_fma_f32 v43, -v41, v42, 1.0
	v_fmac_f32_e32 v42, v43, v42
	v_div_scale_f32 v43, vcc, 1.0, v1, 1.0
	v_mul_f32_e32 v44, v43, v42
	v_fma_f32 v45, -v41, v44, v43
	v_fmac_f32_e32 v44, v45, v42
	v_fma_f32 v41, -v41, v44, v43
	v_div_fmas_f32 v41, v41, v42, v44
	v_div_fixup_f32 v42, v41, v1, 1.0
	v_lshlrev_b64 v[44:45], 12, v[54:55]
	v_pk_fma_f32 v[30:31], v[136:137], v[40:41], v[30:31] op_sel_hi:[1,0,1]
	v_pk_fma_f32 v[32:33], v[126:127], v[40:41], v[32:33] op_sel_hi:[1,0,1]
	v_pk_fma_f32 v[26:27], v[128:129], v[40:41], v[26:27] op_sel_hi:[1,0,1]
	v_pk_fma_f32 v[28:29], v[122:123], v[40:41], v[28:29] op_sel_hi:[1,0,1]
	v_lshl_add_u64 v[44:45], s[42:43], 0, v[44:45]
	v_pk_fma_f32 v[32:33], v[32:33], v[42:43], v[150:151] op_sel_hi:[1,0,1]
	v_pk_fma_f32 v[30:31], v[30:31], v[42:43], v[148:149] op_sel_hi:[1,0,1]
	v_pk_fma_f32 v[46:47], v[28:29], v[42:43], v[154:155] op_sel_hi:[1,0,1]
	v_pk_fma_f32 v[28:29], v[26:27], v[42:43], v[152:153] op_sel_hi:[1,0,1]
	v_lshl_add_u64 v[44:45], v[44:45], 0, v[134:135]
	v_cvt_pk_bf16_f32 v26, v30, v31
	v_cvt_pk_bf16_f32 v27, v32, v33
	v_cvt_pk_bf16_f32 v28, v28, v29
	v_cvt_pk_bf16_f32 v29, v46, v47
	v_pk_fma_f32 v[22:23], v[124:125], v[40:41], v[22:23] op_sel_hi:[1,0,1]
	v_pk_fma_f32 v[24:25], v[118:119], v[40:41], v[24:25] op_sel_hi:[1,0,1]
	v_pk_fma_f32 v[18:19], v[120:121], v[40:41], v[18:19] op_sel_hi:[1,0,1]
	v_pk_fma_f32 v[20:21], v[114:115], v[40:41], v[20:21] op_sel_hi:[1,0,1]
	flat_store_dwordx4 v[44:45], v[26:29]
	v_pk_fma_f32 v[24:25], v[24:25], v[42:43], v[158:159] op_sel_hi:[1,0,1]
	v_pk_fma_f32 v[22:23], v[22:23], v[42:43], v[156:157] op_sel_hi:[1,0,1]
	v_pk_fma_f32 v[26:27], v[20:21], v[42:43], v[182:183] op_sel_hi:[1,0,1]
	v_pk_fma_f32 v[20:21], v[18:19], v[42:43], v[172:173] op_sel_hi:[1,0,1]
	v_cvt_pk_bf16_f32 v18, v22, v23
	v_cvt_pk_bf16_f32 v19, v24, v25
	v_cvt_pk_bf16_f32 v20, v20, v21
	v_cvt_pk_bf16_f32 v21, v26, v27
	flat_store_dwordx4 v[44:45], v[18:21] offset:256
	s_waitcnt vmcnt(0) lgkmcnt(0)
	s_nop 0
	v_cvt_f64_i32_e32 v[18:19], v35
	v_ldexp_f64 v[18:19], v[18:19], 32
	v_cvt_f64_u32_e32 v[20:21], v34
	v_add_f64 v[18:19], v[18:19], v[20:21]
	v_ldexp_f64 v[18:19], v[18:19], s33
	v_cvt_f32_f64_e32 v1, v[18:19]
	v_cvt_f64_i32_e32 v[18:19], v37
	v_ldexp_f64 v[18:19], v[18:19], 32
	v_cvt_f64_u32_e32 v[20:21], v36
	v_add_f64 v[18:19], v[18:19], v[20:21]
	v_ldexp_f64 v[18:19], v[18:19], s33
	v_cvt_f32_f64_e32 v19, v[18:19]
	v_mul_f32_e32 v18, 0x3a000000, v1
	v_mul_f32_e32 v1, v18, v18
	v_fma_f32 v1, v19, s5, -v1
	v_add_f32_e32 v1, 0x3727c5ac, v1
	v_cmp_gt_f32_e32 vcc, s4, v1
	v_mul_f32_e32 v19, 0x4f800000, v1
	s_nop 0
	v_cndmask_b32_e32 v1, v1, v19, vcc
	v_sqrt_f32_e32 v19, v1
	s_nop 0
	v_add_u32_e32 v20, -1, v19
	v_fma_f32 v21, -v20, v19, v1
	v_cmp_ge_f32_e64 s[38:39], 0, v21
	v_add_u32_e32 v21, 1, v19
	s_nop 0
	v_cndmask_b32_e64 v20, v19, v20, s[38:39]
	v_fma_f32 v19, -v21, v19, v1
	v_cmp_lt_f32_e64 s[38:39], 0, v19
	s_nop 1
	v_cndmask_b32_e64 v19, v20, v21, s[38:39]
	v_mul_f32_e32 v20, 0x37800000, v19
	v_cndmask_b32_e32 v19, v19, v20, vcc
	v_cmp_class_f32_e32 vcc, v1, v229
	s_mov_b64 s[38:39], -1
	s_nop 0
	v_cndmask_b32_e32 v1, v19, v1, vcc
	v_div_scale_f32 v19, s[10:11], v1, v1, 1.0
	v_rcp_f32_e32 v20, v19
	s_nop 0
	v_fma_f32 v21, -v19, v20, 1.0
	v_fmac_f32_e32 v20, v21, v20
	v_div_scale_f32 v21, vcc, 1.0, v1, 1.0
	v_mul_f32_e32 v22, v21, v20
	v_fma_f32 v23, -v19, v22, v21
	v_fmac_f32_e32 v22, v23, v20
	v_fma_f32 v19, -v19, v22, v21
	v_div_fmas_f32 v19, v19, v20, v22
	v_div_fixup_f32 v20, v19, v1, 1.0
	v_lshlrev_b64 v[22:23], 12, v[38:39]
	v_pk_fma_f32 v[14:15], v[136:137], v[18:19], v[14:15] op_sel_hi:[1,0,1]
	v_pk_fma_f32 v[16:17], v[126:127], v[18:19], v[16:17] op_sel_hi:[1,0,1]
	v_pk_fma_f32 v[10:11], v[128:129], v[18:19], v[10:11] op_sel_hi:[1,0,1]
	v_pk_fma_f32 v[12:13], v[122:123], v[18:19], v[12:13] op_sel_hi:[1,0,1]
	v_lshl_add_u64 v[22:23], s[42:43], 0, v[22:23]
	v_pk_fma_f32 v[16:17], v[16:17], v[20:21], v[150:151] op_sel_hi:[1,0,1]
	v_pk_fma_f32 v[14:15], v[14:15], v[20:21], v[148:149] op_sel_hi:[1,0,1]
	v_pk_fma_f32 v[24:25], v[12:13], v[20:21], v[154:155] op_sel_hi:[1,0,1]
	v_pk_fma_f32 v[12:13], v[10:11], v[20:21], v[152:153] op_sel_hi:[1,0,1]
	v_lshl_add_u64 v[22:23], v[22:23], 0, v[134:135]
	v_cvt_pk_bf16_f32 v10, v14, v15
	v_cvt_pk_bf16_f32 v11, v16, v17
	v_cvt_pk_bf16_f32 v12, v12, v13
	v_cvt_pk_bf16_f32 v13, v24, v25
	v_pk_fma_f32 v[6:7], v[124:125], v[18:19], v[6:7] op_sel_hi:[1,0,1]
	v_pk_fma_f32 v[8:9], v[118:119], v[18:19], v[8:9] op_sel_hi:[1,0,1]
	v_pk_fma_f32 v[2:3], v[120:121], v[18:19], v[2:3] op_sel_hi:[1,0,1]
	v_pk_fma_f32 v[4:5], v[114:115], v[18:19], v[4:5] op_sel_hi:[1,0,1]
	flat_store_dwordx4 v[22:23], v[10:13]
	v_pk_fma_f32 v[8:9], v[8:9], v[20:21], v[158:159] op_sel_hi:[1,0,1]
	v_pk_fma_f32 v[6:7], v[6:7], v[20:21], v[156:157] op_sel_hi:[1,0,1]
	v_pk_fma_f32 v[10:11], v[4:5], v[20:21], v[182:183] op_sel_hi:[1,0,1]
	v_pk_fma_f32 v[4:5], v[2:3], v[20:21], v[172:173] op_sel_hi:[1,0,1]
	v_cvt_pk_bf16_f32 v2, v6, v7
	v_cvt_pk_bf16_f32 v3, v8, v9
	v_cvt_pk_bf16_f32 v4, v4, v5
	v_cvt_pk_bf16_f32 v5, v10, v11
	s_andn2_b64 vcc, exec, s[36:37]
	flat_store_dwordx4 v[22:23], v[2:5] offset:256
	s_cbranch_vccnz .LBB0_714
	s_andn2_b64 vcc, exec, s[40:41]
	s_cbranch_vccnz .LBB0_713
	s_barrier
	s_branch .LBB0_713
